# nt hint also on the mLSTM item bulk loads (chunk state, conv rows, v rows: read once per item)
# baseline (speedup 1.0000x reference)
.LBB0_497:
	s_add_i32 s8, s65, s1
	s_ashr_i32 s26, s8, 7
	s_bfe_u32 s25, s65, 0x20005
	s_lshl_b32 s9, s26, 2
	s_or_b32 s12, s9, s25
	v_readlane_b32 s14, v254, 45
	s_ashr_i32 s13, s12, 31
	v_readlane_b32 s15, v254, 46
	s_lshl_b64 s[50:51], s[12:13], 11
	s_mov_b64 s[12:13], -1
	s_and_b64 vcc, exec, s[14:15]
	s_cbranch_vccz .LBB0_549
	s_lshl_b32 s97, s25, 7
	v_or_b32_e32 v10, s97, v138
	v_add_u32_e32 v8, v10, v139
	v_ashrrev_i32_e32 v9, 31, v8
	v_add_u32_e32 v10, v10, v140
	v_lshl_add_u64 v[8:9], v[8:9], 2, s[36:37]
	v_ashrrev_i32_e32 v11, 31, v10
	v_lshl_add_u64 v[10:11], v[10:11], 2, s[36:37]
	global_load_dword v79, v[8:9], off
	global_load_dword v80, v[10:11], off
	v_or_b32_e32 v8, s97, v141
	v_lshlrev_b32_e32 v8, 2, v8
	global_load_dword v78, v8, s[88:89]
	s_ashr_i32 s27, s26, 31
	v_readlane_b32 s72, v251, 4
	s_lshl_b64 s[12:13], s[26:27], 23
	v_readlane_b32 s86, v251, 18
	v_readlane_b32 s87, v251, 19
	s_add_u32 s9, s86, s12
	s_addc_u32 s13, s87, s13
	s_and_b32 s12, s65, 0x7f
	s_mul_i32 s12, s12, 0x9000
	s_add_u32 s12, s9, s12
	s_addc_u32 s13, s13, 0
	v_mov_b32_e32 v40, 0
	s_waitcnt lgkmcnt(0)
	v_mov_b32_e32 v44, 0
	v_mov_b32_e32 v45, 0
	v_mov_b32_e32 v46, 0
	v_mov_b32_e32 v47, 0
	v_readlane_b32 s73, v251, 5
	v_readlane_b32 s74, v251, 6
	v_readlane_b32 s75, v251, 7
	v_readlane_b32 s76, v251, 8
	v_readlane_b32 s77, v251, 9
	v_readlane_b32 s78, v251, 10
	v_readlane_b32 s79, v251, 11
	v_readlane_b32 s80, v251, 12
	v_readlane_b32 s81, v251, 13
	v_readlane_b32 s82, v251, 14
	v_readlane_b32 s83, v251, 15
	v_readlane_b32 s84, v251, 16
	v_readlane_b32 s85, v251, 17
	s_mov_b64 s[14:15], exec
	v_readlane_b32 s16, v254, 47
	v_readlane_b32 s17, v254, 48
	s_and_b64 s[16:17], s[14:15], s[16:17]
	s_mov_b64 exec, s[16:17]
	s_cbranch_execz .LBB0_500
	v_lshl_add_u64 v[8:9], v[186:187], 4, s[12:13]
	global_load_dwordx4 v[44:47], v[8:9], off nt
.LBB0_500:
	s_or_b64 exec, exec, s[14:15]
	v_mov_b32_e32 v41, 0
	v_mov_b32_e32 v42, 0
	v_mov_b32_e32 v43, 0
	s_mov_b64 s[14:15], exec
	v_readlane_b32 s16, v254, 49
	v_readlane_b32 s17, v254, 50
	s_and_b64 s[16:17], s[14:15], s[16:17]
	s_mov_b64 exec, s[16:17]
	s_cbranch_execz .LBB0_502
	v_lshl_add_u64 v[8:9], v[110:111], 4, s[12:13]
	global_load_dwordx4 v[40:43], v[8:9], off nt
.LBB0_502:
	s_or_b64 exec, exec, s[14:15]
	v_mov_b32_e32 v48, 0
	v_mov_b32_e32 v56, 0
	v_mov_b32_e32 v57, 0
	v_mov_b32_e32 v58, 0
	v_mov_b32_e32 v59, 0
	s_mov_b64 s[14:15], exec
	v_readlane_b32 s16, v254, 51
	v_readlane_b32 s17, v254, 52
	v_readlane_b32 s84, v254, 37
	v_readlane_b32 s86, v254, 39
	s_and_b64 s[16:17], s[14:15], s[16:17]
	v_readlane_b32 s85, v254, 38
	v_readlane_b32 s87, v254, 40
	s_mov_b64 exec, s[16:17]
	s_cbranch_execz .LBB0_504
	v_lshl_add_u64 v[8:9], v[112:113], 4, s[12:13]
	global_load_dwordx4 v[56:59], v[8:9], off nt
.LBB0_504:
	s_or_b64 exec, exec, s[14:15]
	v_mov_b32_e32 v49, 0
	v_mov_b32_e32 v50, 0
	v_mov_b32_e32 v51, 0
	s_mov_b64 s[14:15], exec
	v_readlane_b32 s16, v254, 53
	v_readlane_b32 s17, v254, 54
	s_and_b64 s[16:17], s[14:15], s[16:17]
	s_mov_b64 exec, s[16:17]
	s_cbranch_execz .LBB0_506
	v_lshl_add_u64 v[8:9], v[114:115], 4, s[12:13]
	global_load_dwordx4 v[48:51], v[8:9], off nt
.LBB0_506:
	s_or_b64 exec, exec, s[14:15]
	v_mov_b32_e32 v52, 0
	v_mov_b32_e32 v64, 0
	v_mov_b32_e32 v65, 0
	v_mov_b32_e32 v66, 0
	v_mov_b32_e32 v67, 0
	s_and_saveexec_b64 s[14:15], s[58:59]
	s_cbranch_execz .LBB0_508
	v_lshl_add_u64 v[8:9], v[116:117], 4, s[12:13]
	global_load_dwordx4 v[64:67], v[8:9], off nt
.LBB0_508:
	s_or_b64 exec, exec, s[14:15]
	s_lshl_b32 s9, s65, 6
	s_and_b32 s9, s9, 0x7c0
	v_add_u32_e32 v180, s9, v143
	s_lshl_b32 s90, s97, 1
	s_lshl_b64 s[52:53], s[26:27], 11
	v_lshl_add_u64 v[68:69], v[118:119], 0, s[90:91]
	v_cmp_lt_i32_e32 vcc, -1, v180
	v_mov_b32_e32 v53, 0
	v_mov_b32_e32 v54, 0
	v_mov_b32_e32 v55, 0
	s_and_saveexec_b64 s[12:13], vcc
	s_cbranch_execz .LBB0_510
	v_lshl_add_u64 v[8:9], s[52:53], 0, v[180:181]
	s_movk_i32 s16, 0x1c00
	v_mad_u64_u32 v[10:11], s[14:15], v8, s16, v[68:69]
	v_mad_i32_i24 v11, v9, s16, v11
	global_load_dwordx4 v[52:55], v[10:11], off offset:3072 nt
.LBB0_510:
	s_or_b64 exec, exec, s[12:13]
	v_add_u32_e32 v12, 1, v180
	v_cmp_lt_i32_e64 s[18:19], -2, v180
	v_mov_b32_e32 v36, 0
	v_mov_b32_e32 v60, 0
	v_mov_b32_e32 v61, 0
	v_mov_b32_e32 v62, 0
	v_mov_b32_e32 v63, 0
	s_and_saveexec_b64 s[12:13], s[18:19]
	s_cbranch_execz .LBB0_512
	v_mov_b32_e32 v13, v181
	v_lshl_add_u64 v[8:9], s[52:53], 0, v[12:13]
	s_movk_i32 s16, 0x1c00
	v_mad_u64_u32 v[10:11], s[14:15], v8, s16, v[68:69]
	v_mad_i32_i24 v11, v9, s16, v11
	global_load_dwordx4 v[60:63], v[10:11], off offset:3072 nt
.LBB0_512:
	s_or_b64 exec, exec, s[12:13]
	v_add_u32_e32 v10, 2, v180
	v_cmp_lt_i32_e64 s[16:17], -3, v180
	v_mov_b32_e32 v37, 0
	v_mov_b32_e32 v38, 0
	v_mov_b32_e32 v39, 0
	s_and_saveexec_b64 s[12:13], s[16:17]
	s_cbranch_execz .LBB0_514
	v_mov_b32_e32 v11, v181
	v_lshl_add_u64 v[8:9], s[52:53], 0, v[10:11]
	s_movk_i32 s27, 0x1c00
	v_mad_u64_u32 v[14:15], s[14:15], v8, s27, v[68:69]
	v_mad_i32_i24 v15, v9, s27, v15
	global_load_dwordx4 v[36:39], v[14:15], off offset:3072 nt
.LBB0_514:
	s_or_b64 exec, exec, s[12:13]
	v_add_u32_e32 v8, s9, v142
	v_cmp_lt_i32_e64 s[14:15], -1, v8
	v_mov_b32_e32 v28, 0
	v_mov_b32_e32 v32, 0
	v_mov_b32_e32 v33, 0
	v_mov_b32_e32 v34, 0
	v_mov_b32_e32 v35, 0
	s_and_saveexec_b64 s[12:13], s[14:15]
	s_cbranch_execz .LBB0_516
	v_mov_b32_e32 v9, v181
	v_lshl_add_u64 v[14:15], s[52:53], 0, v[8:9]
	s_movk_i32 s27, 0x1c00
	v_mad_u64_u32 v[16:17], s[40:41], v14, s27, v[68:69]
	v_mad_i32_i24 v17, v15, s27, v17
	global_load_dwordx4 v[32:35], v[16:17], off offset:3072 nt
.LBB0_516:
	s_or_b64 exec, exec, s[12:13]
	v_add_u32_e32 v70, 4, v180
	v_cmp_lt_i32_e64 s[12:13], -5, v180
	v_mov_b32_e32 v29, 0
	v_mov_b32_e32 v30, 0
	v_mov_b32_e32 v31, 0
	s_and_saveexec_b64 s[54:55], s[12:13]
	s_cbranch_execz .LBB0_518
	v_mov_b32_e32 v71, v181
	v_lshl_add_u64 v[14:15], s[52:53], 0, v[70:71]
	s_movk_i32 s27, 0x1c00
	v_mad_u64_u32 v[16:17], s[40:41], v14, s27, v[68:69]
	v_mad_i32_i24 v17, v15, s27, v17
	global_load_dwordx4 v[28:31], v[16:17], off offset:3072 nt
.LBB0_518:
	s_or_b64 exec, exec, s[54:55]
	v_mov_b32_e32 v20, 0
	v_mov_b32_e32 v24, 0
	v_mov_b32_e32 v25, 0
	v_mov_b32_e32 v26, 0
	v_mov_b32_e32 v27, 0
	s_and_saveexec_b64 s[54:55], vcc
	s_cbranch_execz .LBB0_520
	v_lshl_add_u64 v[14:15], s[52:53], 0, v[180:181]
	s_movk_i32 s27, 0x1c00
	v_mad_u64_u32 v[16:17], s[40:41], v14, s27, v[68:69]
	v_mad_i32_i24 v9, v15, s27, v17
	v_add_co_u32_e32 v14, vcc, 0x1000, v16
	s_nop 1
	v_addc_co_u32_e32 v15, vcc, 0, v9, vcc
	global_load_dwordx4 v[24:27], v[14:15], off nt
.LBB0_520:
	s_or_b64 exec, exec, s[54:55]
	v_mov_b32_e32 v21, 0
	v_mov_b32_e32 v22, 0
	v_mov_b32_e32 v23, 0
	s_and_saveexec_b64 s[54:55], s[18:19]
	s_cbranch_execz .LBB0_522
	v_mov_b32_e32 v13, v181
	v_lshl_add_u64 v[12:13], s[52:53], 0, v[12:13]
	s_movk_i32 s27, 0x1c00
	v_mad_u64_u32 v[14:15], s[18:19], v12, s27, v[68:69]
	v_mad_i32_i24 v9, v13, s27, v15
	v_add_co_u32_e32 v12, vcc, 0x1000, v14
	s_nop 1
	v_addc_co_u32_e32 v13, vcc, 0, v9, vcc
	global_load_dwordx4 v[20:23], v[12:13], off nt
.LBB0_522:
	s_or_b64 exec, exec, s[54:55]
	v_mov_b32_e32 v12, 0
	v_mov_b32_e32 v16, 0
	v_mov_b32_e32 v17, 0
	v_mov_b32_e32 v18, 0
	v_mov_b32_e32 v19, 0
	s_and_saveexec_b64 s[18:19], s[16:17]
	s_cbranch_execz .LBB0_524
	v_mov_b32_e32 v11, v181
	v_lshl_add_u64 v[10:11], s[52:53], 0, v[10:11]
	s_movk_i32 s27, 0x1c00
	v_mad_u64_u32 v[14:15], s[16:17], v10, s27, v[68:69]
	v_mad_i32_i24 v9, v11, s27, v15
	v_add_co_u32_e32 v10, vcc, 0x1000, v14
	s_nop 1
	v_addc_co_u32_e32 v11, vcc, 0, v9, vcc
	global_load_dwordx4 v[16:19], v[10:11], off nt
.LBB0_524:
	s_or_b64 exec, exec, s[18:19]
	v_mov_b32_e32 v13, 0
	v_mov_b32_e32 v14, 0
	v_mov_b32_e32 v15, 0
	s_and_saveexec_b64 s[16:17], s[14:15]
	s_cbranch_execz .LBB0_526
	v_mov_b32_e32 v9, v181
	v_lshl_add_u64 v[8:9], s[52:53], 0, v[8:9]
	s_movk_i32 s18, 0x1c00
	v_mad_u64_u32 v[10:11], s[14:15], v8, s18, v[68:69]
	v_mad_i32_i24 v9, v9, s18, v11
	v_add_co_u32_e32 v8, vcc, 0x1000, v10
	s_nop 1
	v_addc_co_u32_e32 v9, vcc, 0, v9, vcc
	global_load_dwordx4 v[12:15], v[8:9], off nt
.LBB0_526:
	s_or_b64 exec, exec, s[16:17]
	v_mov_b32_e32 v76, 0
	v_mov_b32_e32 v8, 0
	v_mov_b32_e32 v9, 0
	v_mov_b32_e32 v10, 0
	v_mov_b32_e32 v11, 0
	s_and_saveexec_b64 s[14:15], s[12:13]
	s_cbranch_execz .LBB0_528
	v_mov_b32_e32 v71, v181
	v_lshl_add_u64 v[8:9], s[52:53], 0, v[70:71]
	s_movk_i32 s16, 0x1c00
	v_mad_u64_u32 v[10:11], s[12:13], v8, s16, v[68:69]
	v_mad_i32_i24 v9, v9, s16, v11
	v_add_co_u32_e32 v8, vcc, 0x1000, v10
	s_nop 1
	v_addc_co_u32_e32 v9, vcc, 0, v9, vcc
	global_load_dwordx4 v[8:11], v[8:9], off nt
.LBB0_528:
	s_or_b64 exec, exec, s[14:15]
	s_or_b32 s52, s52, s9
	v_lshl_add_u64 v[68:69], s[52:53], 0, v[104:105]
	v_mov_b64_e32 v[70:71], s[4:5]
	s_movk_i32 s14, 0x1c00
	v_mad_u64_u32 v[70:71], s[12:13], v68, s14, v[70:71]
	v_mad_i32_i24 v71, v69, s14, v71
	v_lshl_add_u64 v[68:69], v[70:71], 0, s[90:91]
	v_lshlrev_b32_e32 v180, 1, v120
	v_lshl_add_u64 v[68:69], v[68:69], 0, v[180:181]
	s_mov_b64 s[12:13], 0x1400
	v_lshl_add_u64 v[70:71], v[68:69], 0, s[12:13]
	v_add_co_u32_e32 v68, vcc, 0x1000, v68
	v_cndmask_b32_e64 v77, 0, 1, s[6:7]
	s_nop 0
	v_addc_co_u32_e32 v69, vcc, 0, v69, vcc
	global_load_dwordx4 v[72:75], v[68:69], off offset:1024 nt
	s_nop 0
	global_load_dwordx4 v[68:71], v[70:71], off offset:16 nt
	v_cmp_ne_u32_e64 s[12:13], 1, v77
	s_andn2_b64 vcc, exec, s[6:7]
	v_mov_b32_e32 v77, 0
	s_cbranch_vccnz .LBB0_530
	s_lshl_b64 s[14:15], s[50:51], 2
	v_readlane_b32 s16, v251, 60
	s_add_u32 s16, s16, s14
	v_readlane_b32 s17, v251, 61
	s_addc_u32 s17, s17, s15
	v_readlane_b32 s18, v251, 62
	v_or_b32_e32 v76, s9, v188
	s_add_u32 s14, s18, s14
	v_readlane_b32 s18, v251, 63
	v_lshlrev_b32_e32 v76, 2, v76
	s_addc_u32 s15, s18, s15
	global_load_dword v77, v76, s[16:17]
	s_nop 0
	global_load_dword v76, v76, s[14:15]
.LBB0_530:
	v_or_b32_e32 v182, s52, v122
	v_mov_b64_e32 v[184:185], s[4:5]
	v_mov_b32_e32 v183, 0x1c00
	s_mul_i32 s100, s53, 0x1c00
	v_mad_u64_u32 v[184:185], vcc, v182, v183, v[184:185]
	s_lshl_b32 s101, s97, 2
	v_add_u32_e32 v185, s100, v185
	v_lshl_add_u64 v[184:185], v[184:185], 0, s[90:91]
	v_readlane_b32 s100, v255, 17
	v_lshlrev_b64 v[192:193], 1, v[126:127]
	v_lshlrev_b64 v[194:195], 1, v[128:129]
	s_add_u32 s100, s100, s101
	v_readlane_b32 s101, v255, 18
	v_lshlrev_b64 v[196:197], 1, v[124:125]
	v_add_co_u32_e32 v184, vcc, 0x1800, v184
	s_addc_u32 s101, s101, 0
	s_nop 0
	v_addc_co_u32_e32 v185, vcc, 0, v185, vcc
	v_lshl_add_u64 v[192:193], v[184:185], 0, v[192:193]
	v_lshl_add_u64 v[194:195], v[184:185], 0, v[194:195]
	v_lshl_add_u64 v[196:197], v[184:185], 0, v[196:197]
	global_load_dwordx2 v[92:93], v[192:193], off nt
	global_load_dwordx2 v[94:95], v[194:195], off offset:32 nt
	global_load_dwordx2 v[96:97], v[194:195], off offset:64 nt
	global_load_dwordx2 v[98:99], v[196:197], off nt
	v_lshl_add_u64 v[192:193], v[126:127], 2, s[100:101]
	v_lshl_add_u64 v[194:195], v[128:129], 2, s[100:101]
	v_lshl_add_u64 v[196:197], v[124:125], 2, s[100:101]
	global_load_dwordx4 v[224:227], v[192:193], off nt
	global_load_dwordx4 v[228:231], v[194:195], off offset:64 nt
	global_load_dwordx4 v[232:235], v[194:195], off offset:128 nt
	global_load_dwordx4 v[236:239], v[196:197], off nt
	s_waitcnt vmcnt(24)
	ds_write2st64_b32 v144, v79, v80 offset1:8
	s_and_saveexec_b64 s[14:15], s[58:59]
	ds_write_b32 v144, v78 offset:4096
	s_or_b64 exec, exec, s[14:15]
	s_waitcnt lgkmcnt(0)
	s_barrier
	s_mov_b64 s[14:15], exec
	v_readlane_b32 s16, v254, 55
	v_readlane_b32 s17, v254, 56
	s_and_b64 s[16:17], s[14:15], s[16:17]
	s_mov_b64 exec, s[16:17]
	s_cbranch_execz .LBB0_534
	v_mov_b32_e32 v78, 0x3f803f80
	s_nop 0
	v_mov_b32_e32 v79, v78
	v_mov_b32_e32 v80, v78
	v_mov_b32_e32 v81, v78
	ds_write_b128 v145, v[78:81] offset:35072

.LBB0_549:
	s_and_b64 vcc, exec, s[12:13]
	s_cbranch_vccz .LBB0_571
	s_lshl_b32 s16, s25, 7
	v_or_b32_e32 v8, s16, v138
	v_add_u32_e32 v8, v8, v139
	v_ashrrev_i32_e32 v9, 31, v8
	v_lshl_add_u64 v[10:11], v[8:9], 2, s[36:37]
	v_add_u32_e32 v8, 0x200, v8
	v_ashrrev_i32_e32 v9, 31, v8
	v_lshl_add_u64 v[8:9], v[8:9], 2, s[36:37]
	global_load_dword v37, v[10:11], off
	global_load_dword v40, v[8:9], off
	v_or_b32_e32 v8, s16, v141
	v_lshlrev_b32_e32 v8, 2, v8
	global_load_dword v36, v8, s[88:89]
	s_lshl_b32 s9, s65, 6
	s_and_b32 s9, s9, 0x7c0
	s_ashr_i32 s27, s26, 31
	v_add_u32_e32 v180, s9, v160
	s_lshl_b32 s90, s25, 8
	s_lshl_b64 s[12:13], s[26:27], 11
	v_lshl_add_u64 v[28:29], v[118:119], 0, s[90:91]
	v_cmp_lt_i32_e32 vcc, -1, v180
	v_mov_b32_e32 v20, 0
	v_mov_b32_e32 v24, 0
	v_mov_b32_e32 v25, 0
	v_mov_b32_e32 v26, 0
	v_mov_b32_e32 v27, 0
	s_and_saveexec_b64 s[14:15], vcc
	s_cbranch_execz .LBB0_552
	v_lshl_add_u64 v[8:9], s[12:13], 0, v[180:181]
	s_movk_i32 s17, 0x1c00
	v_mad_u64_u32 v[10:11], s[18:19], v8, s17, v[28:29]
	v_mad_i32_i24 v9, v9, s17, v11
	v_add_co_u32_e32 v8, vcc, 0x1000, v10
	s_nop 1
	v_addc_co_u32_e32 v9, vcc, 0, v9, vcc
	global_load_dwordx4 v[24:27], v[8:9], off nt
.LBB0_552:
	s_or_b64 exec, exec, s[14:15]
	v_cmp_lt_i32_e32 vcc, -2, v180
	v_mov_b32_e32 v21, 0
	v_mov_b32_e32 v22, 0
	v_mov_b32_e32 v23, 0
	s_and_saveexec_b64 s[14:15], vcc
	s_cbranch_execz .LBB0_554
	v_add_u32_e32 v8, 1, v180
	v_mov_b32_e32 v9, v181
	v_lshl_add_u64 v[8:9], s[12:13], 0, v[8:9]
	s_movk_i32 s17, 0x1c00
	v_mad_u64_u32 v[10:11], s[18:19], v8, s17, v[28:29]
	v_mad_i32_i24 v9, v9, s17, v11
	v_add_co_u32_e32 v8, vcc, 0x1000, v10
	s_nop 1
	v_addc_co_u32_e32 v9, vcc, 0, v9, vcc
	global_load_dwordx4 v[20:23], v[8:9], off nt
.LBB0_554:
	s_or_b64 exec, exec, s[14:15]
	v_cmp_lt_i32_e32 vcc, -3, v180
	v_mov_b32_e32 v12, 0
	v_mov_b32_e32 v16, 0
	v_mov_b32_e32 v17, 0
	v_mov_b32_e32 v18, 0
	v_mov_b32_e32 v19, 0
	s_and_saveexec_b64 s[14:15], vcc
	s_cbranch_execz .LBB0_556
	v_add_u32_e32 v8, 2, v180
	v_mov_b32_e32 v9, v181
	v_lshl_add_u64 v[8:9], s[12:13], 0, v[8:9]
	s_movk_i32 s17, 0x1c00
	v_mad_u64_u32 v[10:11], s[18:19], v8, s17, v[28:29]
	v_mad_i32_i24 v9, v9, s17, v11
	v_add_co_u32_e32 v8, vcc, 0x1000, v10
	s_nop 1
	v_addc_co_u32_e32 v9, vcc, 0, v9, vcc
	global_load_dwordx4 v[16:19], v[8:9], off nt
.LBB0_556:
	s_or_b64 exec, exec, s[14:15]
	v_add_u32_e32 v8, s9, v159
	v_cmp_lt_i32_e32 vcc, -1, v8
	v_mov_b32_e32 v13, 0
	v_mov_b32_e32 v14, 0
	v_mov_b32_e32 v15, 0
	s_and_saveexec_b64 s[14:15], vcc
	s_cbranch_execz .LBB0_558
	v_mov_b32_e32 v9, v181
	v_lshl_add_u64 v[8:9], s[12:13], 0, v[8:9]
	s_movk_i32 s17, 0x1c00
	v_mad_u64_u32 v[10:11], s[18:19], v8, s17, v[28:29]
	v_mad_i32_i24 v9, v9, s17, v11
	v_add_co_u32_e32 v8, vcc, 0x1000, v10
	s_nop 1
	v_addc_co_u32_e32 v9, vcc, 0, v9, vcc
	global_load_dwordx4 v[12:15], v[8:9], off nt
.LBB0_558:
	s_or_b64 exec, exec, s[14:15]
	v_cmp_lt_i32_e32 vcc, -5, v180
	v_mov_b32_e32 v38, 0
	v_mov_b32_e32 v8, 0
	v_mov_b32_e32 v9, 0
	v_mov_b32_e32 v10, 0
	v_mov_b32_e32 v11, 0
	s_and_saveexec_b64 s[14:15], vcc
	s_cbranch_execz .LBB0_560
	v_add_u32_e32 v180, 4, v180
	v_lshl_add_u64 v[8:9], s[12:13], 0, v[180:181]
	s_movk_i32 s17, 0x1c00
	v_mad_u64_u32 v[10:11], s[18:19], v8, s17, v[28:29]
	v_mad_i32_i24 v9, v9, s17, v11
	v_add_co_u32_e32 v8, vcc, 0x1000, v10
	s_nop 1
	v_addc_co_u32_e32 v9, vcc, 0, v9, vcc
	global_load_dwordx4 v[8:11], v[8:9], off nt
.LBB0_560:
	s_or_b64 exec, exec, s[14:15]
	s_add_u32 s12, s12, s9
	s_addc_u32 s13, s13, 0
	v_lshl_add_u64 v[28:29], s[12:13], 0, v[104:105]
	v_mov_b64_e32 v[30:31], s[4:5]
	s_movk_i32 s14, 0x1c00
	v_mad_u64_u32 v[30:31], s[12:13], v28, s14, v[30:31]
	v_mad_i32_i24 v31, v29, s14, v31
	s_lshl_b32 s90, s16, 1
	v_lshl_add_u64 v[28:29], v[30:31], 0, s[90:91]
	v_lshlrev_b32_e32 v180, 1, v120
	v_lshl_add_u64 v[28:29], v[28:29], 0, v[180:181]
	s_mov_b64 s[12:13], 0x1400
	v_lshl_add_u64 v[30:31], v[28:29], 0, s[12:13]
	v_add_co_u32_e32 v28, vcc, 0x1000, v28
	v_cndmask_b32_e64 v39, 0, 1, s[6:7]
	s_nop 0
	v_addc_co_u32_e32 v29, vcc, 0, v29, vcc
	global_load_dwordx4 v[32:35], v[28:29], off offset:1024 nt
	s_nop 0
	global_load_dwordx4 v[28:31], v[30:31], off offset:16 nt
	v_cmp_ne_u32_e64 s[12:13], 1, v39
	s_andn2_b64 vcc, exec, s[6:7]
	v_mov_b32_e32 v39, 0
	s_cbranch_vccnz .LBB0_562
	s_lshl_b64 s[14:15], s[50:51], 2
	v_readlane_b32 s16, v251, 60
	s_add_u32 s16, s16, s14
	v_readlane_b32 s17, v251, 61
	s_addc_u32 s17, s17, s15
	v_or_b32_e32 v38, s9, v188
	v_readlane_b32 s9, v251, 62
	v_lshlrev_b32_e32 v38, 2, v38
	s_add_u32 s14, s9, s14
	v_readlane_b32 s9, v251, 63
	s_addc_u32 s15, s9, s15
	global_load_dword v39, v38, s[16:17]
	s_nop 0
	global_load_dword v38, v38, s[14:15]
